# GEMM main loop: one static s_setprio 1 for waves 0-3 at loop entry (mirror of previous), per-phase flips removed
# speedup vs baseline: 1.0067x; 1.0009x over previous
; __device__ __forceinline__ void gemm_phase(LAS unsigned char* lds, const Gemm g, const StaticOrder& S, const Epi& E) {
;     ...
; #pragma unroll
;         for (int a = 0; a < 2; ++a)
; #pragma unroll
;             for (int b = 0; b < 2; ++b)
; #pragma unroll
;                 for (int m = 0; m < 4; ++m)
; #pragma unroll
;                     for (int n = 0; n < 2; ++n) acc[a][b][m][n] = (f32x4){0.f, 0.f, 0.f, 0.f};
;         cur = nxt; cA = nA; cB = nB; ++ui;
.LBB0_761:
	s_add_u32 s0, s34, 0x80
	s_addc_u32 s1, s35, 0
	s_add_u32 s27, s36, 0x100
	v_mov_b32_e32 v0, 0
	s_addc_u32 s33, s37, 0
	s_mov_b32 s34, 0
	v_mov_b32_e32 v1, v0
	v_mov_b32_e32 v2, v0
	v_mov_b32_e32 v3, v0
	v_mov_b32_e32 v4, v0
	v_mov_b32_e32 v5, v0
	v_mov_b32_e32 v6, v0
	v_mov_b32_e32 v7, v0
	v_mov_b32_e32 v16, v0
	v_mov_b32_e32 v17, v0
	v_mov_b32_e32 v18, v0
	v_mov_b32_e32 v19, v0
	s_waitcnt vmcnt(0)
	v_mov_b32_e32 v20, v0
	v_mov_b32_e32 v21, v0
	v_mov_b32_e32 v22, v0
	v_mov_b32_e32 v23, v0
	v_mov_b32_e32 v32, v0
	v_mov_b32_e32 v33, v0
	v_mov_b32_e32 v34, v0
	v_mov_b32_e32 v35, v0
	v_mov_b32_e32 v36, v0
	v_mov_b32_e32 v37, v0
	v_mov_b32_e32 v38, v0
	v_mov_b32_e32 v39, v0
	v_mov_b32_e32 v48, v0
	v_mov_b32_e32 v49, v0
	v_mov_b32_e32 v50, v0
	v_mov_b32_e32 v51, v0
	v_mov_b32_e32 v52, v0
	v_mov_b32_e32 v53, v0
	v_mov_b32_e32 v54, v0
	v_mov_b32_e32 v55, v0
	v_mov_b32_e32 v8, v0
	v_mov_b32_e32 v9, v0
	v_mov_b32_e32 v10, v0
	v_mov_b32_e32 v11, v0
	v_mov_b32_e32 v12, v0
	v_mov_b32_e32 v13, v0
	v_mov_b32_e32 v14, v0
	v_mov_b32_e32 v15, v0
	v_mov_b32_e32 v24, v0
	v_mov_b32_e32 v25, v0
	v_mov_b32_e32 v26, v0
	v_mov_b32_e32 v27, v0
	v_mov_b32_e32 v28, v0
	v_mov_b32_e32 v29, v0
	v_mov_b32_e32 v30, v0
	v_mov_b32_e32 v31, v0
	v_mov_b32_e32 v40, v0
	v_mov_b32_e32 v41, v0
	v_mov_b32_e32 v42, v0
	v_mov_b32_e32 v43, v0
	v_mov_b32_e32 v44, v0
	v_mov_b32_e32 v45, v0
	v_mov_b32_e32 v46, v0
	v_mov_b32_e32 v47, v0
	v_mov_b32_e32 v56, v0
	v_mov_b32_e32 v57, v0
	v_mov_b32_e32 v58, v0
	v_mov_b32_e32 v59, v0
	v_mov_b32_e32 v60, v0
	v_mov_b32_e32 v61, v0
	v_mov_b32_e32 v62, v0
	v_mov_b32_e32 v63, v0
	v_mov_b32_e32 v64, v0
	v_mov_b32_e32 v65, v0
	v_mov_b32_e32 v66, v0
	v_mov_b32_e32 v67, v0
	v_mov_b32_e32 v68, v0
	v_mov_b32_e32 v69, v0
	v_mov_b32_e32 v70, v0
	v_mov_b32_e32 v71, v0
	v_mov_b32_e32 v80, v0
	v_mov_b32_e32 v81, v0
	v_mov_b32_e32 v82, v0
	v_mov_b32_e32 v83, v0
	v_mov_b32_e32 v84, v0
	v_mov_b32_e32 v85, v0
	v_mov_b32_e32 v86, v0
	v_mov_b32_e32 v87, v0
	v_mov_b32_e32 v96, v0
	v_mov_b32_e32 v97, v0
	v_mov_b32_e32 v98, v0
	v_mov_b32_e32 v99, v0
	v_mov_b32_e32 v100, v0
	v_mov_b32_e32 v101, v0
	v_mov_b32_e32 v102, v0
	v_mov_b32_e32 v103, v0
	v_mov_b32_e32 v112, v0
	v_mov_b32_e32 v113, v0
	v_mov_b32_e32 v114, v0
	v_mov_b32_e32 v115, v0
	v_mov_b32_e32 v116, v0
	v_mov_b32_e32 v117, v0
	v_mov_b32_e32 v118, v0
	v_mov_b32_e32 v119, v0
	v_mov_b32_e32 v72, v0
	v_mov_b32_e32 v73, v0
	v_mov_b32_e32 v74, v0
	v_mov_b32_e32 v75, v0
	v_mov_b32_e32 v76, v0
	v_mov_b32_e32 v77, v0
	v_mov_b32_e32 v78, v0
	v_mov_b32_e32 v79, v0
	v_mov_b32_e32 v88, v0
	v_mov_b32_e32 v89, v0
	v_mov_b32_e32 v90, v0
	v_mov_b32_e32 v91, v0
	v_mov_b32_e32 v92, v0
	v_mov_b32_e32 v93, v0
	v_mov_b32_e32 v94, v0
	v_mov_b32_e32 v95, v0
	v_mov_b32_e32 v104, v0
	v_mov_b32_e32 v105, v0
	v_mov_b32_e32 v106, v0
	v_mov_b32_e32 v107, v0
	v_mov_b32_e32 v108, v0
	v_mov_b32_e32 v109, v0
	v_mov_b32_e32 v110, v0
	v_mov_b32_e32 v111, v0
	v_mov_b32_e32 v120, v0
	v_mov_b32_e32 v121, v0
	v_mov_b32_e32 v122, v0
	v_mov_b32_e32 v123, v0
	v_mov_b32_e32 v124, v0
	v_mov_b32_e32 v125, v0
	v_mov_b32_e32 v126, v0
	v_mov_b32_e32 v127, v0
	s_cmpk_gt_u32 s57, 0xff
	s_cbranch_scc1 .Lprio_skip
	s_setprio 1
